# phase 0 prologue: the ten silu(embedding) values per thread are loaded with ten loads in flight instead of a load-wait-compute loop
# baseline (speedup 1.0000x reference)
; #define LAS __attribute__((address_space(3)))
; __global__ void __launch_bounds__(512) mega(Params p) {
;     ...
;             LAS float* sv = (LAS float*)lds; LAS float* red = (LAS float*)(lds + 20480);
;             for (int i = tid; i < 5 * 1024; i += 512) { const float v = i < 4096 ? p.in[1][i] : p.in[3][i - 4096]; sv[i] = v / (1.f + __expf(-v)); }
;             __syncthreads();
.LBB0_619:
	s_waitcnt lgkmcnt(0)
	v_readlane_b32 s28, v253, 61
	s_and_b64 vcc, exec, s[4:5]
	v_readlane_b32 s29, v253, 62
	s_cbranch_vccz .LBB0_681
	v_mov_b32_e32 v10, v242
	s_movk_i32 s1, 0x1400
	v_ashrrev_i32_e32 v0, 6, v10
	v_cmp_gt_i32_e32 vcc, s1, v10
	v_readfirstlane_b32 s0, v0
	s_and_saveexec_b64 s[4:5], vcc
	s_cbranch_execz .LBB0_627
	s_load_dwordx2 s[2:3], s[90:91], 0x8
	s_load_dwordx2 s[6:7], s[90:91], 0x18
	v_lshlrev_b32_e32 v1, 2, v10
	v_add_u32_e32 v2, 0x1000, v1
	v_add_u32_e32 v3, 0x2000, v1
	v_add_u32_e32 v4, 0x3000, v1
	s_waitcnt lgkmcnt(0)
	global_load_dword v20, v1, s[2:3]
	global_load_dword v21, v1, s[2:3] offset:2048
	global_load_dword v22, v2, s[2:3]
	global_load_dword v23, v2, s[2:3] offset:2048
	global_load_dword v24, v3, s[2:3]
	global_load_dword v25, v3, s[2:3] offset:2048
	global_load_dword v26, v4, s[2:3]
	global_load_dword v27, v4, s[2:3] offset:2048
	global_load_dword v28, v1, s[6:7]
	global_load_dword v29, v1, s[6:7] offset:2048
	s_waitcnt vmcnt(9)
	v_mul_f32_e32 v5, 0xbfb8aa3b, v20
	v_exp_f32_e32 v5, v5
	s_nop 0
	v_add_f32_e32 v5, 1.0, v5
	v_div_scale_f32 v7, s[2:3], v5, v5, v20
	v_rcp_f32_e32 v8, v7
	v_div_scale_f32 v9, vcc, v20, v5, v20
	v_fma_f32 v11, -v7, v8, 1.0
	v_fmac_f32_e32 v8, v11, v8
	v_mul_f32_e32 v11, v9, v8
	v_fma_f32 v12, -v7, v11, v9
	v_fmac_f32_e32 v11, v12, v8
	v_fma_f32 v7, -v7, v11, v9
	v_div_fmas_f32 v7, v7, v8, v11
	v_div_fixup_f32 v6, v7, v5, v20
	ds_write_b32 v1, v6
	s_waitcnt vmcnt(8)
	v_mul_f32_e32 v5, 0xbfb8aa3b, v21
	v_exp_f32_e32 v5, v5
	s_nop 0
	v_add_f32_e32 v5, 1.0, v5
	v_div_scale_f32 v7, s[2:3], v5, v5, v21
	v_rcp_f32_e32 v8, v7
	v_div_scale_f32 v9, vcc, v21, v5, v21
	v_fma_f32 v11, -v7, v8, 1.0
	v_fmac_f32_e32 v8, v11, v8
	v_mul_f32_e32 v11, v9, v8
	v_fma_f32 v12, -v7, v11, v9
	v_fmac_f32_e32 v11, v12, v8
	v_fma_f32 v7, -v7, v11, v9
	v_div_fmas_f32 v7, v7, v8, v11
	v_div_fixup_f32 v6, v7, v5, v21
	ds_write_b32 v1, v6 offset:2048
	s_waitcnt vmcnt(7)
	v_mul_f32_e32 v5, 0xbfb8aa3b, v22
	v_exp_f32_e32 v5, v5
	s_nop 0
	v_add_f32_e32 v5, 1.0, v5
	v_div_scale_f32 v7, s[2:3], v5, v5, v22
	v_rcp_f32_e32 v8, v7
	v_div_scale_f32 v9, vcc, v22, v5, v22
	v_fma_f32 v11, -v7, v8, 1.0
	v_fmac_f32_e32 v8, v11, v8
	v_mul_f32_e32 v11, v9, v8
	v_fma_f32 v12, -v7, v11, v9
	v_fmac_f32_e32 v11, v12, v8
	v_fma_f32 v7, -v7, v11, v9
	v_div_fmas_f32 v7, v7, v8, v11
	v_div_fixup_f32 v6, v7, v5, v22
	ds_write_b32 v1, v6 offset:4096
	s_waitcnt vmcnt(6)
	v_mul_f32_e32 v5, 0xbfb8aa3b, v23
	v_exp_f32_e32 v5, v5
	s_nop 0
	v_add_f32_e32 v5, 1.0, v5
	v_div_scale_f32 v7, s[2:3], v5, v5, v23
	v_rcp_f32_e32 v8, v7
	v_div_scale_f32 v9, vcc, v23, v5, v23
	v_fma_f32 v11, -v7, v8, 1.0
	v_fmac_f32_e32 v8, v11, v8
	v_mul_f32_e32 v11, v9, v8
	v_fma_f32 v12, -v7, v11, v9
	v_fmac_f32_e32 v11, v12, v8
	v_fma_f32 v7, -v7, v11, v9
	v_div_fmas_f32 v7, v7, v8, v11
	v_div_fixup_f32 v6, v7, v5, v23
	ds_write_b32 v1, v6 offset:6144
	s_waitcnt vmcnt(5)
	v_mul_f32_e32 v5, 0xbfb8aa3b, v24
	v_exp_f32_e32 v5, v5
	s_nop 0
	v_add_f32_e32 v5, 1.0, v5
	v_div_scale_f32 v7, s[2:3], v5, v5, v24
	v_rcp_f32_e32 v8, v7
	v_div_scale_f32 v9, vcc, v24, v5, v24
	v_fma_f32 v11, -v7, v8, 1.0
	v_fmac_f32_e32 v8, v11, v8
	v_mul_f32_e32 v11, v9, v8
	v_fma_f32 v12, -v7, v11, v9
	v_fmac_f32_e32 v11, v12, v8
	v_fma_f32 v7, -v7, v11, v9
	v_div_fmas_f32 v7, v7, v8, v11
	v_div_fixup_f32 v6, v7, v5, v24
	ds_write_b32 v1, v6 offset:8192
	s_waitcnt vmcnt(4)
	v_mul_f32_e32 v5, 0xbfb8aa3b, v25
	v_exp_f32_e32 v5, v5
	s_nop 0
	v_add_f32_e32 v5, 1.0, v5
	v_div_scale_f32 v7, s[2:3], v5, v5, v25
	v_rcp_f32_e32 v8, v7
	v_div_scale_f32 v9, vcc, v25, v5, v25
	v_fma_f32 v11, -v7, v8, 1.0
	v_fmac_f32_e32 v8, v11, v8
	v_mul_f32_e32 v11, v9, v8
	v_fma_f32 v12, -v7, v11, v9
	v_fmac_f32_e32 v11, v12, v8
	v_fma_f32 v7, -v7, v11, v9
	v_div_fmas_f32 v7, v7, v8, v11
	v_div_fixup_f32 v6, v7, v5, v25
	ds_write_b32 v1, v6 offset:10240
	s_waitcnt vmcnt(3)
	v_mul_f32_e32 v5, 0xbfb8aa3b, v26
	v_exp_f32_e32 v5, v5
	s_nop 0
	v_add_f32_e32 v5, 1.0, v5
	v_div_scale_f32 v7, s[2:3], v5, v5, v26
	v_rcp_f32_e32 v8, v7
	v_div_scale_f32 v9, vcc, v26, v5, v26
	v_fma_f32 v11, -v7, v8, 1.0
	v_fmac_f32_e32 v8, v11, v8
	v_mul_f32_e32 v11, v9, v8
	v_fma_f32 v12, -v7, v11, v9
	v_fmac_f32_e32 v11, v12, v8
	v_fma_f32 v7, -v7, v11, v9
	v_div_fmas_f32 v7, v7, v8, v11
	v_div_fixup_f32 v6, v7, v5, v26
	ds_write_b32 v1, v6 offset:12288
	s_waitcnt vmcnt(2)
	v_mul_f32_e32 v5, 0xbfb8aa3b, v27
	v_exp_f32_e32 v5, v5
	s_nop 0
	v_add_f32_e32 v5, 1.0, v5
	v_div_scale_f32 v7, s[2:3], v5, v5, v27
	v_rcp_f32_e32 v8, v7
	v_div_scale_f32 v9, vcc, v27, v5, v27
	v_fma_f32 v11, -v7, v8, 1.0
	v_fmac_f32_e32 v8, v11, v8
	v_mul_f32_e32 v11, v9, v8
	v_fma_f32 v12, -v7, v11, v9
	v_fmac_f32_e32 v11, v12, v8
	v_fma_f32 v7, -v7, v11, v9
	v_div_fmas_f32 v7, v7, v8, v11
	v_div_fixup_f32 v6, v7, v5, v27
	ds_write_b32 v1, v6 offset:14336
	s_waitcnt vmcnt(1)
	v_mul_f32_e32 v5, 0xbfb8aa3b, v28
	v_exp_f32_e32 v5, v5
	s_nop 0
	v_add_f32_e32 v5, 1.0, v5
	v_div_scale_f32 v7, s[2:3], v5, v5, v28
	v_rcp_f32_e32 v8, v7
	v_div_scale_f32 v9, vcc, v28, v5, v28
	v_fma_f32 v11, -v7, v8, 1.0
	v_fmac_f32_e32 v8, v11, v8
	v_mul_f32_e32 v11, v9, v8
	v_fma_f32 v12, -v7, v11, v9
	v_fmac_f32_e32 v11, v12, v8
	v_fma_f32 v7, -v7, v11, v9
	v_div_fmas_f32 v7, v7, v8, v11
	v_div_fixup_f32 v6, v7, v5, v28
	ds_write_b32 v1, v6 offset:16384
	s_waitcnt vmcnt(0)
	v_mul_f32_e32 v5, 0xbfb8aa3b, v29
	v_exp_f32_e32 v5, v5
	s_nop 0
	v_add_f32_e32 v5, 1.0, v5
	v_div_scale_f32 v7, s[2:3], v5, v5, v29
	v_rcp_f32_e32 v8, v7
	v_div_scale_f32 v9, vcc, v29, v5, v29
	v_fma_f32 v11, -v7, v8, 1.0
	v_fmac_f32_e32 v8, v11, v8
	v_mul_f32_e32 v11, v9, v8
	v_fma_f32 v12, -v7, v11, v9
	v_fmac_f32_e32 v11, v12, v8
	v_fma_f32 v7, -v7, v11, v9
	v_div_fmas_f32 v7, v7, v8, v11
	v_div_fixup_f32 v6, v7, v5, v29
	ds_write_b32 v1, v6 offset:18432
